# P3 step A (qkv short conv + SiLU + L2 norms) hand-written: packed-f32 FMAs for the conv, DPP norm reductions, ~840 instead of ~1330 instructions; same f32 arithmetic and bf16 rounding points
# speedup vs baseline: 1.0144x; 1.0144x over previous
; #define LAS __attribute__((address_space(3)))
; __device__ __forceinline__ float exp_f(float x) { return __builtin_amdgcn_exp2f(x * 1.4426950408889634f); }
; #define LBAR() do { asm volatile("s_waitcnt lgkmcnt(0)" ::: "memory"); __builtin_amdgcn_s_barrier(); asm volatile("" ::: "memory"); } while (0)
; __device__ __forceinline__ void prep_task(LAS unsigned char* lds, const PrepP& P, int task, int tid, int lane, int wave) {
;     ...
;     LBAR();
;     {
;         const int t = tid >> 3, seg = tid & 7;
;         const float beta = gcl[64 + t], gc = gcl[t], glc = gcl[63];
;         const float eg = exp_f(gc), et = exp_f(glc - gc);
;         const int tt = n * 64 + t;
;         const bf16_t* zr = P.z + (size_t)(row0 + t) * NZ + 4096 + h * 128 + seg * 16;
;         const LAS float* cw = (const LAS float*)(lds + 114688) + seg * 16;
;         u32x4 xz[3][2][4];
; #pragma unroll
;         for (int m = 0; m < 3; ++m)
; #pragma unroll
;             for (int hf = 0; hf < 2; ++hf)
; #pragma unroll
;                 for (int j = 0; j < 4; ++j) { const bool ok = tt - 3 + j >= 0; xz[m][hf][j] = *(const u32x4*)(zr + m * 1024 + hf * 8 + (ptrdiff_t)(ok ? j - 3 : 0) * NZ); if (!ok) xz[m][hf][j] = (u32x4){0u, 0u, 0u, 0u}; }
;         const int lo = t * PS + seg * 16;
;         float x[16], y[16];
;         { float o[8]; conv8(xz[2][0], cw + 256, o);
.LBB0_420:
	v_ashrrev_i32_e32 v26, 3, v55
	v_add_u32_e32 v0, s8, v26
	v_ashrrev_i32_e32 v1, 31, v0
	v_lshlrev_b64 v[0:1], 14, v[0:1]
	v_lshlrev_b32_e32 v2, 4, v55
	v_lshl_add_u64 v[0:1], v[40:41], 0, v[0:1]
	v_and_b32_e32 v60, 0x70, v2
	v_lshl_add_u64 v[0:1], v[0:1], 0, s[38:39]
	v_lshlrev_b32_e32 v152, 1, v60
	v_lshl_add_u64 v[4:5], v[0:1], 0, v[152:153]
	s_mov_b64 s[6:7], 0x13c02000
	s_and_b32 s9, s49, 0x7c0
	v_lshl_add_u64 v[6:7], v[4:5], 0, s[6:7]
	v_add_co_u32_e64 v12, s[6:7], s76, v4
	v_add_u32_e32 v27, s9, v26
	s_nop 0
	v_addc_co_u32_e64 v13, s[6:7], 0, v5, s[6:7]
	v_cmp_lt_i32_e32 vcc, 2, v27
	v_mov_b32_e32 v0, 0xffff4000
	v_cmp_lt_i32_e64 s[6:7], 0, v27
	v_cndmask_b32_e32 v8, 0, v0, vcc
	v_cmp_lt_i32_e64 s[8:9], 1, v27
	v_cndmask_b32_e64 v0, 0, -1, s[6:7]
	v_mov_b32_e32 v1, v0
	s_mov_b64 s[10:11], 0x13c03000
	v_cndmask_b32_e64 v9, 0, -1, vcc
	v_cndmask_b32_e64 v15, 0, -1, s[8:9]
	v_cndmask_b32_e64 v14, 0, v197, s[8:9]
	v_lshlrev_b64 v[24:25], 14, v[0:1]
	v_lshl_add_u64 v[32:33], v[4:5], 0, s[10:11]
	s_waitcnt lgkmcnt(0)
	s_barrier
	s_load_dwordx2 s[6:7], s[0:1], 0x98
	s_lshr_b32 s14, s49, 11
	s_lshr_b32 s11, s2, 3
	s_and_b32 s11, s11, 31
	s_lshl_b32 s15, s14, 11
	s_lshl_b32 s10, s11, 6
	s_add_i32 s15, s15, s10
	v_add_u32_e32 v27, s10, v26
	v_add_u32_e32 v57, s15, v26
	v_and_b32_e32 v28, 7, v55
	v_lshlrev_b32_e32 v57, 14, v57
	s_and_b32 s15, s2, 7
	s_lshl_b32 s15, s15, 8
	s_addk_i32 s15, 0x2800
	v_lshl_add_u32 v29, v28, 5, s15
	v_add_u32_e32 v57, v57, v29
	v_min_u32_e32 v59, 3, v27
	v_lshlrev_b32_e32 v59, 14, v59
	v_sub_u32_e32 v59, v57, v59
	v_min_u32_e32 v61, 2, v27
	v_lshlrev_b32_e32 v61, 14, v61
	v_sub_u32_e32 v61, v57, v61
	v_min_u32_e32 v1, 1, v27
	v_lshlrev_b32_e32 v1, 14, v1
	v_sub_u32_e32 v1, v57, v1
	v_lshl_add_u32 v36, v28, 6, v58
	v_add_u32_e32 v36, 0x1c000, v36
	v_mul_u32_u24_e32 v37, 0x110, v26
	v_lshl_add_u32 v37, v28, 5, v37
	v_add_u32_e32 v37, v37, v58
	v_add_u32_e32 v38, 0xcc00, v37
	v_lshlrev_b32_e32 v39, 8, v26
	v_lshl_add_u32 v39, v28, 5, v39
	v_lshl_add_u32 v30, v26, 2, v63
	v_add_u32_e32 v31, 0x1b8fc, v58
	ds_read2st64_b32 v[32:33], v30 offset1:1
	ds_read_b32 v53, v31
	s_waitcnt lgkmcnt(0)
	s_add_u32 s6, s6, 0x13c00000
	s_addc_u32 s7, s7, 0
	global_load_dwordx4 v[64:67], v59, s[6:7] offset:-2048
	global_load_dwordx4 v[80:83], v59, s[6:7] offset:-2032
	global_load_dwordx4 v[96:99], v59, s[6:7]
	global_load_dwordx4 v[112:115], v59, s[6:7] offset:16
	global_load_dwordx4 v[128:131], v59, s[6:7] offset:2048
	global_load_dwordx4 v[144:147], v59, s[6:7] offset:2064
	global_load_dwordx4 v[68:71], v61, s[6:7] offset:-2048
	global_load_dwordx4 v[84:87], v61, s[6:7] offset:-2032
	global_load_dwordx4 v[100:103], v61, s[6:7]
	global_load_dwordx4 v[116:119], v61, s[6:7] offset:16
	global_load_dwordx4 v[132:135], v61, s[6:7] offset:2048
	global_load_dwordx4 v[148:151], v61, s[6:7] offset:2064
	global_load_dwordx4 v[72:75], v1, s[6:7] offset:-2048
	global_load_dwordx4 v[88:91], v1, s[6:7] offset:-2032
	global_load_dwordx4 v[104:107], v1, s[6:7]
	global_load_dwordx4 v[120:123], v1, s[6:7] offset:16
	global_load_dwordx4 v[136:139], v1, s[6:7] offset:2048
	global_load_dwordx4 v[156:159], v1, s[6:7] offset:2064
	global_load_dwordx4 v[76:79], v57, s[6:7] offset:-2048
	global_load_dwordx4 v[92:95], v57, s[6:7] offset:-2032
	global_load_dwordx4 v[108:111], v57, s[6:7]
	global_load_dwordx4 v[124:127], v57, s[6:7] offset:16
	global_load_dwordx4 v[140:143], v57, s[6:7] offset:2048
	global_load_dwordx4 v[160:163], v57, s[6:7] offset:2064
	s_lshl_b32 s15, s14, 8
	s_add_i32 s15, s15, s2
	s_mul_hi_u32 s9, s15, 0x1a000
	s_mul_i32 s8, s15, 0x1a000
	s_add_u32 s8, s8, s6
	s_addc_u32 s9, s9, s7
	s_add_u32 s8, s8, 0xe804000
	s_addc_u32 s9, s9, 0
	s_mov_b32 s10, 0xffff0000
	v_mov_b32_e32 v252, 0xbfb8aa3b
	v_mov_b32_e32 v253, 0xbfb8aa3b
	s_mov_b32 s14, 1.0
	s_mov_b32 s15, 1.0
	v_mov_b32_e32 v51, v32
	v_mov_b32_e32 v50, v33
	v_sub_f32_e32 v24, v53, v51
	v_mul_f32_e32 v52, 0x3fb8aa3b, v51
	v_mul_f32_e32 v24, 0x3fb8aa3b, v24
	v_exp_f32_e32 v52, v52
	v_exp_f32_e32 v24, v24
	s_nop 0
	v_mul_f32_e32 v62, v50, v52
	ds_read_b128 v[164:167], v36 offset:1024
	ds_read_b128 v[168:171], v36 offset:1040
	ds_read_b128 v[172:175], v36 offset:2560
	ds_read_b128 v[176:179], v36 offset:2576
	ds_read_b128 v[180:183], v36 offset:4096
	ds_read_b128 v[184:187], v36 offset:4112
	ds_read_b128 v[188:191], v36 offset:5632
	ds_read_b128 v[200:203], v36 offset:5648
	s_waitcnt vmcnt(0)
	s_cmp_lg_u32 s11, 0
	s_cbranch_scc1 .Lstepa_nomask
; #define LAS __attribute__((address_space(3)))
; __device__ __forceinline__ u32x4 pack8(const float* v) { u32x4 o; o.x = pk2(v[0], v[1]); o.y = pk2(v[2], v[3]); o.z = pk2(v[4], v[5]); o.w = pk2(v[6], v[7]); return o; }
; __device__ __forceinline__ void prep_task(LAS unsigned char* lds, const PrepP& P, int task, int tid, int lane, int wave) {
;     ...
;                 for (int j = 0; j < 4; ++j) { const bool ok = tt - 3 + j >= 0; xz[m][hf][j] = *(const u32x4*)(zr + m * 1024 + hf * 8 + (ptrdiff_t)(ok ? j - 3 : 0) * NZ); if (!ok) xz[m][hf][j] = (u32x4){0u, 0u, 0u, 0u}; }
;         const int lo = t * PS + seg * 16;
;         float x[16], y[16];
;         { float o[8]; conv8(xz[2][0], cw + 256, o);
; #pragma unroll
;           for (int i = 0; i < 8; ++i) x[i] = o[i] * beta;
;           conv8(xz[2][1], cw + 256 + 8, o);
; #pragma unroll
;           for (int i = 0; i < 8; ++i) x[8 + i] = o[i] * beta; }
;         *(LAS u32x4*)(Vl + lo) = pack8(x); *(LAS u32x4*)(Vl + lo + 8) = pack8(x + 8);
	v_cmp_gt_u32_e32 vcc, 3, v27
	s_nop 1
	v_cndmask_b32_e64 v64, v64, 0, vcc
	v_cndmask_b32_e64 v65, v65, 0, vcc
	v_cndmask_b32_e64 v66, v66, 0, vcc
	v_cndmask_b32_e64 v67, v67, 0, vcc
	v_cndmask_b32_e64 v80, v80, 0, vcc
	v_cndmask_b32_e64 v81, v81, 0, vcc
	v_cndmask_b32_e64 v82, v82, 0, vcc
	v_cndmask_b32_e64 v83, v83, 0, vcc
	v_cndmask_b32_e64 v96, v96, 0, vcc
	v_cndmask_b32_e64 v97, v97, 0, vcc
	v_cndmask_b32_e64 v98, v98, 0, vcc
	v_cndmask_b32_e64 v99, v99, 0, vcc
	v_cndmask_b32_e64 v112, v112, 0, vcc
	v_cndmask_b32_e64 v113, v113, 0, vcc
	v_cndmask_b32_e64 v114, v114, 0, vcc
	v_cndmask_b32_e64 v115, v115, 0, vcc
	v_cndmask_b32_e64 v128, v128, 0, vcc
	v_cndmask_b32_e64 v129, v129, 0, vcc
	v_cndmask_b32_e64 v130, v130, 0, vcc
	v_cndmask_b32_e64 v131, v131, 0, vcc
	v_cndmask_b32_e64 v144, v144, 0, vcc
	v_cndmask_b32_e64 v145, v145, 0, vcc
	v_cndmask_b32_e64 v146, v146, 0, vcc
	v_cndmask_b32_e64 v147, v147, 0, vcc
	v_cmp_gt_u32_e32 vcc, 2, v27
	s_nop 1
	v_cndmask_b32_e64 v68, v68, 0, vcc
	v_cndmask_b32_e64 v69, v69, 0, vcc
	v_cndmask_b32_e64 v70, v70, 0, vcc
	v_cndmask_b32_e64 v71, v71, 0, vcc
	v_cndmask_b32_e64 v84, v84, 0, vcc
	v_cndmask_b32_e64 v85, v85, 0, vcc
	v_cndmask_b32_e64 v86, v86, 0, vcc
	v_cndmask_b32_e64 v87, v87, 0, vcc
	v_cndmask_b32_e64 v100, v100, 0, vcc
	v_cndmask_b32_e64 v101, v101, 0, vcc
	v_cndmask_b32_e64 v102, v102, 0, vcc
	v_cndmask_b32_e64 v103, v103, 0, vcc
	v_cndmask_b32_e64 v116, v116, 0, vcc
	v_cndmask_b32_e64 v117, v117, 0, vcc
	v_cndmask_b32_e64 v118, v118, 0, vcc
	v_cndmask_b32_e64 v119, v119, 0, vcc
	v_cndmask_b32_e64 v132, v132, 0, vcc
	v_cndmask_b32_e64 v133, v133, 0, vcc
	v_cndmask_b32_e64 v134, v134, 0, vcc
	v_cndmask_b32_e64 v135, v135, 0, vcc
	v_cndmask_b32_e64 v148, v148, 0, vcc
	v_cndmask_b32_e64 v149, v149, 0, vcc
	v_cndmask_b32_e64 v150, v150, 0, vcc
	v_cndmask_b32_e64 v151, v151, 0, vcc
	v_cmp_gt_u32_e32 vcc, 1, v27
	s_nop 1
	v_cndmask_b32_e64 v72, v72, 0, vcc
	v_cndmask_b32_e64 v73, v73, 0, vcc
	v_cndmask_b32_e64 v74, v74, 0, vcc
	v_cndmask_b32_e64 v75, v75, 0, vcc
	v_cndmask_b32_e64 v88, v88, 0, vcc
	v_cndmask_b32_e64 v89, v89, 0, vcc
	v_cndmask_b32_e64 v90, v90, 0, vcc
	v_cndmask_b32_e64 v91, v91, 0, vcc
	v_cndmask_b32_e64 v104, v104, 0, vcc
	v_cndmask_b32_e64 v105, v105, 0, vcc
	v_cndmask_b32_e64 v106, v106, 0, vcc
	v_cndmask_b32_e64 v107, v107, 0, vcc
	v_cndmask_b32_e64 v120, v120, 0, vcc
	v_cndmask_b32_e64 v121, v121, 0, vcc
	v_cndmask_b32_e64 v122, v122, 0, vcc
	v_cndmask_b32_e64 v123, v123, 0, vcc
	v_cndmask_b32_e64 v136, v136, 0, vcc
	v_cndmask_b32_e64 v137, v137, 0, vcc
	v_cndmask_b32_e64 v138, v138, 0, vcc
	v_cndmask_b32_e64 v139, v139, 0, vcc
	v_cndmask_b32_e64 v156, v156, 0, vcc
	v_cndmask_b32_e64 v157, v157, 0, vcc
	v_cndmask_b32_e64 v158, v158, 0, vcc
	v_cndmask_b32_e64 v159, v159, 0, vcc
.Lstepa_nomask:
	ds_read_b128 v[204:207], v36 offset:1056
	ds_read_b128 v[208:211], v36 offset:1072
	ds_read_b128 v[212:215], v36 offset:2592
	ds_read_b128 v[216:219], v36 offset:2608
	ds_read_b128 v[220:223], v36 offset:4128
	ds_read_b128 v[224:227], v36 offset:4144
	ds_read_b128 v[228:231], v36 offset:5664
	ds_read_b128 v[232:235], v36 offset:5680
	s_waitcnt lgkmcnt(8)
	v_lshlrev_b32_e32 v0, 16, v128
	v_and_b32_e32 v1, s10, v128
	v_lshlrev_b32_e32 v2, 16, v129
	v_and_b32_e32 v3, s10, v129
	v_lshlrev_b32_e32 v4, 16, v130
	v_and_b32_e32 v5, s10, v130
	v_lshlrev_b32_e32 v6, 16, v131
	v_and_b32_e32 v7, s10, v131
	v_pk_mul_f32 v[8:9], v[164:165], v[0:1]
	v_pk_mul_f32 v[10:11], v[166:167], v[2:3]
	v_pk_mul_f32 v[12:13], v[168:169], v[4:5]
	v_pk_mul_f32 v[14:15], v[170:171], v[6:7]
	v_lshlrev_b32_e32 v0, 16, v132
	v_and_b32_e32 v1, s10, v132
	v_lshlrev_b32_e32 v2, 16, v133
	v_and_b32_e32 v3, s10, v133
	v_lshlrev_b32_e32 v4, 16, v134
	v_and_b32_e32 v5, s10, v134
	v_lshlrev_b32_e32 v6, 16, v135
	v_and_b32_e32 v7, s10, v135
	v_pk_fma_f32 v[8:9], v[172:173], v[0:1], v[8:9]
	v_pk_fma_f32 v[10:11], v[174:175], v[2:3], v[10:11]
	v_pk_fma_f32 v[12:13], v[176:177], v[4:5], v[12:13]
	v_pk_fma_f32 v[14:15], v[178:179], v[6:7], v[14:15]
	v_lshlrev_b32_e32 v0, 16, v136
	v_and_b32_e32 v1, s10, v136
	v_lshlrev_b32_e32 v2, 16, v137
	v_and_b32_e32 v3, s10, v137
	v_lshlrev_b32_e32 v4, 16, v138
	v_and_b32_e32 v5, s10, v138
	v_lshlrev_b32_e32 v6, 16, v139
	v_and_b32_e32 v7, s10, v139
	v_pk_fma_f32 v[8:9], v[180:181], v[0:1], v[8:9]
	v_pk_fma_f32 v[10:11], v[182:183], v[2:3], v[10:11]
	v_pk_fma_f32 v[12:13], v[184:185], v[4:5], v[12:13]
	v_pk_fma_f32 v[14:15], v[186:187], v[6:7], v[14:15]
	v_lshlrev_b32_e32 v0, 16, v140
	v_and_b32_e32 v1, s10, v140
	v_lshlrev_b32_e32 v2, 16, v141
	v_and_b32_e32 v3, s10, v141
	v_lshlrev_b32_e32 v4, 16, v142
	v_and_b32_e32 v5, s10, v142
	v_lshlrev_b32_e32 v6, 16, v143
	v_and_b32_e32 v7, s10, v143
	v_pk_fma_f32 v[8:9], v[188:189], v[0:1], v[8:9]
	v_pk_fma_f32 v[10:11], v[190:191], v[2:3], v[10:11]
	v_pk_fma_f32 v[12:13], v[200:201], v[4:5], v[12:13]
	v_pk_fma_f32 v[14:15], v[202:203], v[6:7], v[14:15]
	v_pk_mul_f32 v[16:17], v[8:9], v[252:253]
	v_pk_mul_f32 v[18:19], v[10:11], v[252:253]
	v_pk_mul_f32 v[20:21], v[12:13], v[252:253]
	v_pk_mul_f32 v[22:23], v[14:15], v[252:253]
	v_exp_f32_e32 v16, v16
	v_exp_f32_e32 v17, v17
	v_exp_f32_e32 v18, v18
	v_exp_f32_e32 v19, v19
	v_exp_f32_e32 v20, v20
	v_exp_f32_e32 v21, v21
	v_exp_f32_e32 v22, v22
	v_exp_f32_e32 v23, v23
	v_pk_add_f32 v[16:17], v[16:17], s[14:15]
	v_pk_add_f32 v[18:19], v[18:19], s[14:15]
	v_pk_add_f32 v[20:21], v[20:21], s[14:15]
	v_pk_add_f32 v[22:23], v[22:23], s[14:15]
	v_rcp_f32_e32 v16, v16
	v_rcp_f32_e32 v17, v17
	v_rcp_f32_e32 v18, v18
	v_rcp_f32_e32 v19, v19
	v_rcp_f32_e32 v20, v20
	v_rcp_f32_e32 v21, v21
	v_rcp_f32_e32 v22, v22
	v_rcp_f32_e32 v23, v23
	s_nop 0
	v_pk_mul_f32 v[8:9], v[8:9], v[16:17]
	v_pk_mul_f32 v[10:11], v[10:11], v[18:19]
	v_pk_mul_f32 v[12:13], v[12:13], v[20:21]
	v_pk_mul_f32 v[14:15], v[14:15], v[22:23]
	v_pk_mul_f32 v[8:9], v[8:9], v[50:51] op_sel_hi:[1,0]
	v_pk_mul_f32 v[10:11], v[10:11], v[50:51] op_sel_hi:[1,0]
	v_pk_mul_f32 v[12:13], v[12:13], v[50:51] op_sel_hi:[1,0]
	v_pk_mul_f32 v[14:15], v[14:15], v[50:51] op_sel_hi:[1,0]
	v_cvt_pk_bf16_f32 v28, v8, v9
	v_cvt_pk_bf16_f32 v29, v10, v11
	v_cvt_pk_bf16_f32 v30, v12, v13
	v_cvt_pk_bf16_f32 v31, v14, v15
	ds_write_b128 v37, v[28:31] offset:34816
	ds_read_b128 v[164:167], v36 offset:512
	ds_read_b128 v[168:171], v36 offset:528
	ds_read_b128 v[172:175], v36 offset:2048
	ds_read_b128 v[176:179], v36 offset:2064
	ds_read_b128 v[180:183], v36 offset:3584
	ds_read_b128 v[184:187], v36 offset:3600
	ds_read_b128 v[188:191], v36 offset:5120
	ds_read_b128 v[200:203], v36 offset:5136
	s_waitcnt lgkmcnt(8)
; #define LAS __attribute__((address_space(3)))
; __device__ __forceinline__ u32x4 pack8(const float* v) { u32x4 o; o.x = pk2(v[0], v[1]); o.y = pk2(v[2], v[3]); o.z = pk2(v[4], v[5]); o.w = pk2(v[6], v[7]); return o; }
; __device__ __forceinline__ void prep_task(LAS unsigned char* lds, const PrepP& P, int task, int tid, int lane, int wave) {
;     ...
;         { float o[8]; conv8(xz[2][0], cw + 256, o);
; #pragma unroll
;           for (int i = 0; i < 8; ++i) x[i] = o[i] * beta;
;           conv8(xz[2][1], cw + 256 + 8, o);
; #pragma unroll
;           for (int i = 0; i < 8; ++i) x[8 + i] = o[i] * beta; }
;         *(LAS u32x4*)(Vl + lo) = pack8(x); *(LAS u32x4*)(Vl + lo + 8) = pack8(x + 8);
;         asm volatile("" ::: "memory");
;         { float o[8]; conv8(xz[1][0], cw + 128, o);
; #pragma unroll
;           for (int i = 0; i < 8; ++i) x[i] = o[i];
;           conv8(xz[1][1], cw + 128 + 8, o);
; #pragma unroll
;           for (int i = 0; i < 8; ++i) x[8 + i] = o[i]; }
	v_lshlrev_b32_e32 v0, 16, v144
	v_and_b32_e32 v1, s10, v144
	v_lshlrev_b32_e32 v2, 16, v145
	v_and_b32_e32 v3, s10, v145
	v_lshlrev_b32_e32 v4, 16, v146
	v_and_b32_e32 v5, s10, v146
	v_lshlrev_b32_e32 v6, 16, v147
	v_and_b32_e32 v7, s10, v147
	v_pk_mul_f32 v[8:9], v[204:205], v[0:1]
	v_pk_mul_f32 v[10:11], v[206:207], v[2:3]
	v_pk_mul_f32 v[12:13], v[208:209], v[4:5]
	v_pk_mul_f32 v[14:15], v[210:211], v[6:7]
	v_lshlrev_b32_e32 v0, 16, v148
	v_and_b32_e32 v1, s10, v148
	v_lshlrev_b32_e32 v2, 16, v149
	v_and_b32_e32 v3, s10, v149
	v_lshlrev_b32_e32 v4, 16, v150
	v_and_b32_e32 v5, s10, v150
	v_lshlrev_b32_e32 v6, 16, v151
	v_and_b32_e32 v7, s10, v151
	v_pk_fma_f32 v[8:9], v[212:213], v[0:1], v[8:9]
	v_pk_fma_f32 v[10:11], v[214:215], v[2:3], v[10:11]
	v_pk_fma_f32 v[12:13], v[216:217], v[4:5], v[12:13]
	v_pk_fma_f32 v[14:15], v[218:219], v[6:7], v[14:15]
	v_lshlrev_b32_e32 v0, 16, v156
	v_and_b32_e32 v1, s10, v156
	v_lshlrev_b32_e32 v2, 16, v157
	v_and_b32_e32 v3, s10, v157
	v_lshlrev_b32_e32 v4, 16, v158
	v_and_b32_e32 v5, s10, v158
	v_lshlrev_b32_e32 v6, 16, v159
	v_and_b32_e32 v7, s10, v159
	v_pk_fma_f32 v[8:9], v[220:221], v[0:1], v[8:9]
	v_pk_fma_f32 v[10:11], v[222:223], v[2:3], v[10:11]
	v_pk_fma_f32 v[12:13], v[224:225], v[4:5], v[12:13]
	v_pk_fma_f32 v[14:15], v[226:227], v[6:7], v[14:15]
	v_lshlrev_b32_e32 v0, 16, v160
	v_and_b32_e32 v1, s10, v160
	v_lshlrev_b32_e32 v2, 16, v161
	v_and_b32_e32 v3, s10, v161
	v_lshlrev_b32_e32 v4, 16, v162
	v_and_b32_e32 v5, s10, v162
	v_lshlrev_b32_e32 v6, 16, v163
	v_and_b32_e32 v7, s10, v163
	v_pk_fma_f32 v[8:9], v[228:229], v[0:1], v[8:9]
	v_pk_fma_f32 v[10:11], v[230:231], v[2:3], v[10:11]
	v_pk_fma_f32 v[12:13], v[232:233], v[4:5], v[12:13]
	v_pk_fma_f32 v[14:15], v[234:235], v[6:7], v[14:15]
	v_pk_mul_f32 v[16:17], v[8:9], v[252:253]
	v_pk_mul_f32 v[18:19], v[10:11], v[252:253]
	v_pk_mul_f32 v[20:21], v[12:13], v[252:253]
	v_pk_mul_f32 v[22:23], v[14:15], v[252:253]
	v_exp_f32_e32 v16, v16
	v_exp_f32_e32 v17, v17
	v_exp_f32_e32 v18, v18
	v_exp_f32_e32 v19, v19
	v_exp_f32_e32 v20, v20
	v_exp_f32_e32 v21, v21
	v_exp_f32_e32 v22, v22
	v_exp_f32_e32 v23, v23
	v_pk_add_f32 v[16:17], v[16:17], s[14:15]
	v_pk_add_f32 v[18:19], v[18:19], s[14:15]
	v_pk_add_f32 v[20:21], v[20:21], s[14:15]
	v_pk_add_f32 v[22:23], v[22:23], s[14:15]
	v_rcp_f32_e32 v16, v16
	v_rcp_f32_e32 v17, v17
	v_rcp_f32_e32 v18, v18
	v_rcp_f32_e32 v19, v19
	v_rcp_f32_e32 v20, v20
	v_rcp_f32_e32 v21, v21
	v_rcp_f32_e32 v22, v22
	v_rcp_f32_e32 v23, v23
	s_nop 0
	v_pk_mul_f32 v[8:9], v[8:9], v[16:17]
	v_pk_mul_f32 v[10:11], v[10:11], v[18:19]
	v_pk_mul_f32 v[12:13], v[12:13], v[20:21]
	v_pk_mul_f32 v[14:15], v[14:15], v[22:23]
	v_pk_mul_f32 v[8:9], v[8:9], v[50:51] op_sel_hi:[1,0]
	v_pk_mul_f32 v[10:11], v[10:11], v[50:51] op_sel_hi:[1,0]
	v_pk_mul_f32 v[12:13], v[12:13], v[50:51] op_sel_hi:[1,0]
	v_pk_mul_f32 v[14:15], v[14:15], v[50:51] op_sel_hi:[1,0]
	v_cvt_pk_bf16_f32 v28, v8, v9
	v_cvt_pk_bf16_f32 v29, v10, v11
	v_cvt_pk_bf16_f32 v30, v12, v13
	v_cvt_pk_bf16_f32 v31, v14, v15
	ds_write_b128 v37, v[28:31] offset:34832
	ds_read_b128 v[204:207], v36 offset:544
	ds_read_b128 v[208:211], v36 offset:560
	ds_read_b128 v[212:215], v36 offset:2080
	ds_read_b128 v[216:219], v36 offset:2096
	ds_read_b128 v[220:223], v36 offset:3616
	ds_read_b128 v[224:227], v36 offset:3632
	ds_read_b128 v[228:231], v36 offset:5152
	ds_read_b128 v[232:235], v36 offset:5168
	s_waitcnt lgkmcnt(8)
	v_lshlrev_b32_e32 v0, 16, v96
	v_and_b32_e32 v1, s10, v96
	v_lshlrev_b32_e32 v2, 16, v97
	v_and_b32_e32 v3, s10, v97
	v_lshlrev_b32_e32 v4, 16, v98
	v_and_b32_e32 v5, s10, v98
	v_lshlrev_b32_e32 v6, 16, v99
	v_and_b32_e32 v7, s10, v99
	v_pk_mul_f32 v[8:9], v[164:165], v[0:1]
	v_pk_mul_f32 v[10:11], v[166:167], v[2:3]
	v_pk_mul_f32 v[12:13], v[168:169], v[4:5]
	v_pk_mul_f32 v[14:15], v[170:171], v[6:7]
	v_lshlrev_b32_e32 v0, 16, v100
	v_and_b32_e32 v1, s10, v100
	v_lshlrev_b32_e32 v2, 16, v101
	v_and_b32_e32 v3, s10, v101
	v_lshlrev_b32_e32 v4, 16, v102
	v_and_b32_e32 v5, s10, v102
	v_lshlrev_b32_e32 v6, 16, v103
	v_and_b32_e32 v7, s10, v103
	v_pk_fma_f32 v[8:9], v[172:173], v[0:1], v[8:9]
	v_pk_fma_f32 v[10:11], v[174:175], v[2:3], v[10:11]
	v_pk_fma_f32 v[12:13], v[176:177], v[4:5], v[12:13]
	v_pk_fma_f32 v[14:15], v[178:179], v[6:7], v[14:15]
	v_lshlrev_b32_e32 v0, 16, v104
	v_and_b32_e32 v1, s10, v104
	v_lshlrev_b32_e32 v2, 16, v105
	v_and_b32_e32 v3, s10, v105
	v_lshlrev_b32_e32 v4, 16, v106
	v_and_b32_e32 v5, s10, v106
	v_lshlrev_b32_e32 v6, 16, v107
	v_and_b32_e32 v7, s10, v107
	v_pk_fma_f32 v[8:9], v[180:181], v[0:1], v[8:9]
	v_pk_fma_f32 v[10:11], v[182:183], v[2:3], v[10:11]
	v_pk_fma_f32 v[12:13], v[184:185], v[4:5], v[12:13]
	v_pk_fma_f32 v[14:15], v[186:187], v[6:7], v[14:15]
	v_lshlrev_b32_e32 v0, 16, v108
	v_and_b32_e32 v1, s10, v108
	v_lshlrev_b32_e32 v2, 16, v109
	v_and_b32_e32 v3, s10, v109
	v_lshlrev_b32_e32 v4, 16, v110
	v_and_b32_e32 v5, s10, v110
	v_lshlrev_b32_e32 v6, 16, v111
	v_and_b32_e32 v7, s10, v111
	v_pk_fma_f32 v[8:9], v[188:189], v[0:1], v[8:9]
	v_pk_fma_f32 v[10:11], v[190:191], v[2:3], v[10:11]
	v_pk_fma_f32 v[12:13], v[200:201], v[4:5], v[12:13]
	v_pk_fma_f32 v[14:15], v[202:203], v[6:7], v[14:15]
	v_pk_mul_f32 v[16:17], v[8:9], v[252:253]
	v_pk_mul_f32 v[18:19], v[10:11], v[252:253]
	v_pk_mul_f32 v[20:21], v[12:13], v[252:253]
	v_pk_mul_f32 v[22:23], v[14:15], v[252:253]
	v_exp_f32_e32 v16, v16
	v_exp_f32_e32 v17, v17
	v_exp_f32_e32 v18, v18
	v_exp_f32_e32 v19, v19
	v_exp_f32_e32 v20, v20
	v_exp_f32_e32 v21, v21
	v_exp_f32_e32 v22, v22
	v_exp_f32_e32 v23, v23
	v_pk_add_f32 v[16:17], v[16:17], s[14:15]
	v_pk_add_f32 v[18:19], v[18:19], s[14:15]
	v_pk_add_f32 v[20:21], v[20:21], s[14:15]
	v_pk_add_f32 v[22:23], v[22:23], s[14:15]
	v_rcp_f32_e32 v16, v16
	v_rcp_f32_e32 v17, v17
	v_rcp_f32_e32 v18, v18
	v_rcp_f32_e32 v19, v19
	v_rcp_f32_e32 v20, v20
	v_rcp_f32_e32 v21, v21
	v_rcp_f32_e32 v22, v22
	v_rcp_f32_e32 v23, v23
	s_nop 0
	v_pk_mul_f32 v[236:237], v[8:9], v[16:17]
	v_pk_mul_f32 v[238:239], v[10:11], v[18:19]
	v_pk_mul_f32 v[240:241], v[12:13], v[20:21]
	v_pk_mul_f32 v[242:243], v[14:15], v[22:23]
	ds_read_b128 v[164:167], v36 offset:0
	ds_read_b128 v[168:171], v36 offset:16
	ds_read_b128 v[172:175], v36 offset:1536
	ds_read_b128 v[176:179], v36 offset:1552
	ds_read_b128 v[180:183], v36 offset:3072
	ds_read_b128 v[184:187], v36 offset:3088
	ds_read_b128 v[188:191], v36 offset:4608
	ds_read_b128 v[200:203], v36 offset:4624
	s_waitcnt lgkmcnt(8)
; #define LAS __attribute__((address_space(3)))
; __device__ __forceinline__ float rsq_f(float x) { return __builtin_amdgcn_rsqf(x); }
; __device__ __forceinline__ u32x4 pack8(const float* v) { u32x4 o; o.x = pk2(v[0], v[1]); o.y = pk2(v[2], v[3]); o.z = pk2(v[4], v[5]); o.w = pk2(v[6], v[7]); return o; }
; __device__ __forceinline__ void prep_task(LAS unsigned char* lds, const PrepP& P, int task, int tid, int lane, int wave) {
;     ...
;         { float o[8]; conv8(xz[1][0], cw + 128, o);
; #pragma unroll
;           for (int i = 0; i < 8; ++i) x[i] = o[i];
;           conv8(xz[1][1], cw + 128 + 8, o);
; #pragma unroll
;           for (int i = 0; i < 8; ++i) x[8 + i] = o[i]; }
;         { float sk = 0.f;
; #pragma unroll
;           for (int i = 0; i < 16; ++i) sk += x[i] * x[i];
;           sk += __shfl_xor(sk, 1); sk += __shfl_xor(sk, 2); sk += __shfl_xor(sk, 4);
;           const float rk = rsq_f(sk + EPS);
; #pragma unroll
;           for (int i = 0; i < 16; ++i) x[i] *= rk; }
;         *(LAS u32x4*)(Kl + lo) = pack8(x); *(LAS u32x4*)(Kl + lo + 8) = pack8(x + 8);
; #pragma unroll
;         for (int i = 0; i < 16; ++i) y[i] = x[i] * (beta * eg);
;         *(LAS u32x4*)(KBl + lo) = pack8(y); *(LAS u32x4*)(KBl + lo + 8) = pack8(y + 8);
; #pragma unroll
;         for (int i = 0; i < 16; ++i) y[i] = x[i] * et;
;         *(LAS u32x4*)(KTl + lo) = pack8(y); *(LAS u32x4*)(KTl + lo + 8) = pack8(y + 8);
	v_lshlrev_b32_e32 v0, 16, v112
	v_and_b32_e32 v1, s10, v112
	v_lshlrev_b32_e32 v2, 16, v113
	v_and_b32_e32 v3, s10, v113
	v_lshlrev_b32_e32 v4, 16, v114
	v_and_b32_e32 v5, s10, v114
	v_lshlrev_b32_e32 v6, 16, v115
	v_and_b32_e32 v7, s10, v115
	v_pk_mul_f32 v[8:9], v[204:205], v[0:1]
	v_pk_mul_f32 v[10:11], v[206:207], v[2:3]
	v_pk_mul_f32 v[12:13], v[208:209], v[4:5]
	v_pk_mul_f32 v[14:15], v[210:211], v[6:7]
	v_lshlrev_b32_e32 v0, 16, v116
	v_and_b32_e32 v1, s10, v116
	v_lshlrev_b32_e32 v2, 16, v117
	v_and_b32_e32 v3, s10, v117
	v_lshlrev_b32_e32 v4, 16, v118
	v_and_b32_e32 v5, s10, v118
	v_lshlrev_b32_e32 v6, 16, v119
	v_and_b32_e32 v7, s10, v119
	v_pk_fma_f32 v[8:9], v[212:213], v[0:1], v[8:9]
	v_pk_fma_f32 v[10:11], v[214:215], v[2:3], v[10:11]
	v_pk_fma_f32 v[12:13], v[216:217], v[4:5], v[12:13]
	v_pk_fma_f32 v[14:15], v[218:219], v[6:7], v[14:15]
	v_lshlrev_b32_e32 v0, 16, v120
	v_and_b32_e32 v1, s10, v120
	v_lshlrev_b32_e32 v2, 16, v121
	v_and_b32_e32 v3, s10, v121
	v_lshlrev_b32_e32 v4, 16, v122
	v_and_b32_e32 v5, s10, v122
	v_lshlrev_b32_e32 v6, 16, v123
	v_and_b32_e32 v7, s10, v123
	v_pk_fma_f32 v[8:9], v[220:221], v[0:1], v[8:9]
	v_pk_fma_f32 v[10:11], v[222:223], v[2:3], v[10:11]
	v_pk_fma_f32 v[12:13], v[224:225], v[4:5], v[12:13]
	v_pk_fma_f32 v[14:15], v[226:227], v[6:7], v[14:15]
	v_lshlrev_b32_e32 v0, 16, v124
	v_and_b32_e32 v1, s10, v124
	v_lshlrev_b32_e32 v2, 16, v125
	v_and_b32_e32 v3, s10, v125
	v_lshlrev_b32_e32 v4, 16, v126
	v_and_b32_e32 v5, s10, v126
	v_lshlrev_b32_e32 v6, 16, v127
	v_and_b32_e32 v7, s10, v127
	v_pk_fma_f32 v[8:9], v[228:229], v[0:1], v[8:9]
	v_pk_fma_f32 v[10:11], v[230:231], v[2:3], v[10:11]
	v_pk_fma_f32 v[12:13], v[232:233], v[4:5], v[12:13]
	v_pk_fma_f32 v[14:15], v[234:235], v[6:7], v[14:15]
	v_pk_mul_f32 v[16:17], v[8:9], v[252:253]
	v_pk_mul_f32 v[18:19], v[10:11], v[252:253]
	v_pk_mul_f32 v[20:21], v[12:13], v[252:253]
	v_pk_mul_f32 v[22:23], v[14:15], v[252:253]
	v_exp_f32_e32 v16, v16
	v_exp_f32_e32 v17, v17
	v_exp_f32_e32 v18, v18
	v_exp_f32_e32 v19, v19
	v_exp_f32_e32 v20, v20
	v_exp_f32_e32 v21, v21
	v_exp_f32_e32 v22, v22
	v_exp_f32_e32 v23, v23
	v_pk_add_f32 v[16:17], v[16:17], s[14:15]
	v_pk_add_f32 v[18:19], v[18:19], s[14:15]
	v_pk_add_f32 v[20:21], v[20:21], s[14:15]
	v_pk_add_f32 v[22:23], v[22:23], s[14:15]
	v_rcp_f32_e32 v16, v16
	v_rcp_f32_e32 v17, v17
	v_rcp_f32_e32 v18, v18
	v_rcp_f32_e32 v19, v19
	v_rcp_f32_e32 v20, v20
	v_rcp_f32_e32 v21, v21
	v_rcp_f32_e32 v22, v22
	v_rcp_f32_e32 v23, v23
	s_nop 0
	v_pk_mul_f32 v[244:245], v[8:9], v[16:17]
	v_pk_mul_f32 v[246:247], v[10:11], v[18:19]
	v_pk_mul_f32 v[248:249], v[12:13], v[20:21]
	v_pk_mul_f32 v[250:251], v[14:15], v[22:23]
	v_pk_mul_f32 v[16:17], v[236:237], v[236:237]
	v_pk_fma_f32 v[16:17], v[238:239], v[238:239], v[16:17]
	v_pk_fma_f32 v[16:17], v[240:241], v[240:241], v[16:17]
	v_pk_fma_f32 v[16:17], v[242:243], v[242:243], v[16:17]
	v_pk_fma_f32 v[16:17], v[244:245], v[244:245], v[16:17]
	v_pk_fma_f32 v[16:17], v[246:247], v[246:247], v[16:17]
	v_pk_fma_f32 v[16:17], v[248:249], v[248:249], v[16:17]
	v_pk_fma_f32 v[16:17], v[250:251], v[250:251], v[16:17]
	v_add_f32_e32 v25, v16, v17
	s_nop 1
	v_add_f32_dpp v25, v25, v25 quad_perm:[1,0,3,2] row_mask:0xf bank_mask:0xf bound_ctrl:1
	s_nop 1
	v_add_f32_dpp v25, v25, v25 quad_perm:[2,3,0,1] row_mask:0xf bank_mask:0xf bound_ctrl:1
	s_nop 1
	v_add_f32_dpp v25, v25, v25 row_half_mirror row_mask:0xf bank_mask:0xf bound_ctrl:1
	v_add_f32_e32 v25, 0x358637bd, v25
	v_rsq_f32_e32 v60, v25
	s_nop 0
	v_pk_mul_f32 v[236:237], v[236:237], v[60:61] op_sel_hi:[1,0]
	v_pk_mul_f32 v[238:239], v[238:239], v[60:61] op_sel_hi:[1,0]
	v_pk_mul_f32 v[240:241], v[240:241], v[60:61] op_sel_hi:[1,0]
	v_pk_mul_f32 v[242:243], v[242:243], v[60:61] op_sel_hi:[1,0]
	v_pk_mul_f32 v[244:245], v[244:245], v[60:61] op_sel_hi:[1,0]
	v_pk_mul_f32 v[246:247], v[246:247], v[60:61] op_sel_hi:[1,0]
	v_pk_mul_f32 v[248:249], v[248:249], v[60:61] op_sel_hi:[1,0]
	v_pk_mul_f32 v[250:251], v[250:251], v[60:61] op_sel_hi:[1,0]
	v_cvt_pk_bf16_f32 v28, v236, v237
	v_cvt_pk_bf16_f32 v29, v238, v239
	v_cvt_pk_bf16_f32 v30, v240, v241
	v_cvt_pk_bf16_f32 v31, v242, v243
	ds_write_b128 v37, v[28:31]
	v_cvt_pk_bf16_f32 v28, v244, v245
	v_cvt_pk_bf16_f32 v29, v246, v247
	v_cvt_pk_bf16_f32 v30, v248, v249
	v_cvt_pk_bf16_f32 v31, v250, v251
	ds_write_b128 v37, v[28:31] offset:16
	v_pk_mul_f32 v[8:9], v[236:237], v[62:63] op_sel_hi:[1,0]
	v_pk_mul_f32 v[10:11], v[238:239], v[62:63] op_sel_hi:[1,0]
	v_pk_mul_f32 v[12:13], v[240:241], v[62:63] op_sel_hi:[1,0]
	v_pk_mul_f32 v[14:15], v[242:243], v[62:63] op_sel_hi:[1,0]
	v_cvt_pk_bf16_f32 v28, v8, v9
	v_cvt_pk_bf16_f32 v29, v10, v11
	v_cvt_pk_bf16_f32 v30, v12, v13
	v_cvt_pk_bf16_f32 v31, v14, v15
	ds_write_b128 v38, v[28:31]
	v_pk_mul_f32 v[8:9], v[244:245], v[62:63] op_sel_hi:[1,0]
	v_pk_mul_f32 v[10:11], v[246:247], v[62:63] op_sel_hi:[1,0]
	v_pk_mul_f32 v[12:13], v[248:249], v[62:63] op_sel_hi:[1,0]
	v_pk_mul_f32 v[14:15], v[250:251], v[62:63] op_sel_hi:[1,0]
	v_cvt_pk_bf16_f32 v28, v8, v9
	v_cvt_pk_bf16_f32 v29, v10, v11
	v_cvt_pk_bf16_f32 v30, v12, v13
	v_cvt_pk_bf16_f32 v31, v14, v15
	ds_write_b128 v38, v[28:31] offset:16
	v_pk_mul_f32 v[8:9], v[236:237], v[24:25] op_sel_hi:[1,0]
	v_pk_mul_f32 v[10:11], v[238:239], v[24:25] op_sel_hi:[1,0]
	v_pk_mul_f32 v[12:13], v[240:241], v[24:25] op_sel_hi:[1,0]
	v_pk_mul_f32 v[14:15], v[242:243], v[24:25] op_sel_hi:[1,0]
	v_cvt_pk_bf16_f32 v28, v8, v9
	v_cvt_pk_bf16_f32 v29, v10, v11
	v_cvt_pk_bf16_f32 v30, v12, v13
	v_cvt_pk_bf16_f32 v31, v14, v15
	ds_write_b128 v38, v[28:31] offset:17408
	v_pk_mul_f32 v[8:9], v[244:245], v[24:25] op_sel_hi:[1,0]
	v_pk_mul_f32 v[10:11], v[246:247], v[24:25] op_sel_hi:[1,0]
	v_pk_mul_f32 v[12:13], v[248:249], v[24:25] op_sel_hi:[1,0]
	v_pk_mul_f32 v[14:15], v[250:251], v[24:25] op_sel_hi:[1,0]
	v_cvt_pk_bf16_f32 v28, v8, v9
	v_cvt_pk_bf16_f32 v29, v10, v11
	v_cvt_pk_bf16_f32 v30, v12, v13
	v_cvt_pk_bf16_f32 v31, v14, v15
	ds_write_b128 v38, v[28:31] offset:17424
	ds_read_b128 v[204:207], v36 offset:32
	ds_read_b128 v[208:211], v36 offset:48
	ds_read_b128 v[212:215], v36 offset:1568
	ds_read_b128 v[216:219], v36 offset:1584
	ds_read_b128 v[220:223], v36 offset:3104
	ds_read_b128 v[224:227], v36 offset:3120
	ds_read_b128 v[228:231], v36 offset:4640
	ds_read_b128 v[232:235], v36 offset:4656
	s_waitcnt lgkmcnt(8)
; __device__ __forceinline__ void prep_task(LAS unsigned char* lds, const PrepP& P, int task, int tid, int lane, int wave) {
;     ...
;         { float o[8]; conv8(xz[0][0], cw, o);
; #pragma unroll
;           for (int i = 0; i < 8; ++i) x[i] = o[i];
;           conv8(xz[0][1], cw + 8, o);
; #pragma unroll
;           for (int i = 0; i < 8; ++i) x[8 + i] = o[i]; }
	v_lshlrev_b32_e32 v0, 16, v64
	v_and_b32_e32 v1, s10, v64
	v_lshlrev_b32_e32 v2, 16, v65
	v_and_b32_e32 v3, s10, v65
	v_lshlrev_b32_e32 v4, 16, v66
	v_and_b32_e32 v5, s10, v66
	v_lshlrev_b32_e32 v6, 16, v67
	v_and_b32_e32 v7, s10, v67
	v_pk_mul_f32 v[8:9], v[164:165], v[0:1]
	v_pk_mul_f32 v[10:11], v[166:167], v[2:3]
	v_pk_mul_f32 v[12:13], v[168:169], v[4:5]
	v_pk_mul_f32 v[14:15], v[170:171], v[6:7]
	v_lshlrev_b32_e32 v0, 16, v68
	v_and_b32_e32 v1, s10, v68
	v_lshlrev_b32_e32 v2, 16, v69
	v_and_b32_e32 v3, s10, v69
	v_lshlrev_b32_e32 v4, 16, v70
	v_and_b32_e32 v5, s10, v70
	v_lshlrev_b32_e32 v6, 16, v71
	v_and_b32_e32 v7, s10, v71
	v_pk_fma_f32 v[8:9], v[172:173], v[0:1], v[8:9]
	v_pk_fma_f32 v[10:11], v[174:175], v[2:3], v[10:11]
	v_pk_fma_f32 v[12:13], v[176:177], v[4:5], v[12:13]
	v_pk_fma_f32 v[14:15], v[178:179], v[6:7], v[14:15]
	v_lshlrev_b32_e32 v0, 16, v72
	v_and_b32_e32 v1, s10, v72
	v_lshlrev_b32_e32 v2, 16, v73
	v_and_b32_e32 v3, s10, v73
	v_lshlrev_b32_e32 v4, 16, v74
	v_and_b32_e32 v5, s10, v74
	v_lshlrev_b32_e32 v6, 16, v75
	v_and_b32_e32 v7, s10, v75
	v_pk_fma_f32 v[8:9], v[180:181], v[0:1], v[8:9]
	v_pk_fma_f32 v[10:11], v[182:183], v[2:3], v[10:11]
	v_pk_fma_f32 v[12:13], v[184:185], v[4:5], v[12:13]
	v_pk_fma_f32 v[14:15], v[186:187], v[6:7], v[14:15]
	v_lshlrev_b32_e32 v0, 16, v76
	v_and_b32_e32 v1, s10, v76
	v_lshlrev_b32_e32 v2, 16, v77
	v_and_b32_e32 v3, s10, v77
	v_lshlrev_b32_e32 v4, 16, v78
	v_and_b32_e32 v5, s10, v78
	v_lshlrev_b32_e32 v6, 16, v79
	v_and_b32_e32 v7, s10, v79
	v_pk_fma_f32 v[8:9], v[188:189], v[0:1], v[8:9]
	v_pk_fma_f32 v[10:11], v[190:191], v[2:3], v[10:11]
	v_pk_fma_f32 v[12:13], v[200:201], v[4:5], v[12:13]
	v_pk_fma_f32 v[14:15], v[202:203], v[6:7], v[14:15]
	v_pk_mul_f32 v[16:17], v[8:9], v[252:253]
	v_pk_mul_f32 v[18:19], v[10:11], v[252:253]
	v_pk_mul_f32 v[20:21], v[12:13], v[252:253]
	v_pk_mul_f32 v[22:23], v[14:15], v[252:253]
	v_exp_f32_e32 v16, v16
	v_exp_f32_e32 v17, v17
	v_exp_f32_e32 v18, v18
	v_exp_f32_e32 v19, v19
	v_exp_f32_e32 v20, v20
	v_exp_f32_e32 v21, v21
	v_exp_f32_e32 v22, v22
	v_exp_f32_e32 v23, v23
	v_pk_add_f32 v[16:17], v[16:17], s[14:15]
	v_pk_add_f32 v[18:19], v[18:19], s[14:15]
	v_pk_add_f32 v[20:21], v[20:21], s[14:15]
	v_pk_add_f32 v[22:23], v[22:23], s[14:15]
	v_rcp_f32_e32 v16, v16
	v_rcp_f32_e32 v17, v17
	v_rcp_f32_e32 v18, v18
	v_rcp_f32_e32 v19, v19
	v_rcp_f32_e32 v20, v20
	v_rcp_f32_e32 v21, v21
	v_rcp_f32_e32 v22, v22
	v_rcp_f32_e32 v23, v23
	s_nop 0
	v_pk_mul_f32 v[236:237], v[8:9], v[16:17]
	v_pk_mul_f32 v[238:239], v[10:11], v[18:19]
	v_pk_mul_f32 v[240:241], v[12:13], v[20:21]
	v_pk_mul_f32 v[242:243], v[14:15], v[22:23]
	s_waitcnt lgkmcnt(0)
; #define LAS __attribute__((address_space(3)))
; __device__ __forceinline__ float rsq_f(float x) { return __builtin_amdgcn_rsqf(x); }
; #define LBAR() do { asm volatile("s_waitcnt lgkmcnt(0)" ::: "memory"); __builtin_amdgcn_s_barrier(); asm volatile("" ::: "memory"); } while (0)
; __device__ __forceinline__ u32x4 pack8(const float* v) { u32x4 o; o.x = pk2(v[0], v[1]); o.y = pk2(v[2], v[3]); o.z = pk2(v[4], v[5]); o.w = pk2(v[6], v[7]); return o; }
; __device__ __forceinline__ void prep_task(LAS unsigned char* lds, const PrepP& P, int task, int tid, int lane, int wave) {
;     ...
;           conv8(xz[0][1], cw + 8, o);
; #pragma unroll
;           for (int i = 0; i < 8; ++i) x[8 + i] = o[i]; }
;         { float sq = 0.f;
; #pragma unroll
;           for (int i = 0; i < 16; ++i) sq += x[i] * x[i];
;           sq += __shfl_xor(sq, 1); sq += __shfl_xor(sq, 2); sq += __shfl_xor(sq, 4);
;           const float rq = rsq_f(sq + EPS) * 0.08838834764831845f;
; #pragma unroll
;           for (int i = 0; i < 16; ++i) x[i] *= rq; }
;         *(LAS u32x4*)(Ql + lo) = pack8(x); *(LAS u32x4*)(Ql + lo + 8) = pack8(x + 8);
; #pragma unroll
;         for (int i = 0; i < 16; ++i) y[i] = x[i] * eg;
;         bf16_t* qo = (bf16_t*)(trp + TR_Q) + t * 128 + seg * 16;
;         *(u32x4*)qo = pack8(y); *(u32x4*)(qo + 8) = pack8(y + 8);
;     }
;     LBAR();
;     {
;         const int it = wave >> 1, jt0 = (wave & 1) * 2;
;         bf16x8 aK[4], aQ[4];
; #pragma unroll
;         for (int ks = 0; ks < 4; ++ks) { aK[ks] = *(const LAS bf16x8*)(Kl + (it * 16 + r) * PS + ks * 32 + q8 * 8); aQ[ks] = *(const LAS bf16x8*)(Ql + (it * 16 + r) * PS + ks * 32 + q8 * 8); }
	v_lshlrev_b32_e32 v0, 16, v80
	v_and_b32_e32 v1, s10, v80
	v_lshlrev_b32_e32 v2, 16, v81
	v_and_b32_e32 v3, s10, v81
	v_lshlrev_b32_e32 v4, 16, v82
	v_and_b32_e32 v5, s10, v82
	v_lshlrev_b32_e32 v6, 16, v83
	v_and_b32_e32 v7, s10, v83
	v_pk_mul_f32 v[8:9], v[204:205], v[0:1]
	v_pk_mul_f32 v[10:11], v[206:207], v[2:3]
	v_pk_mul_f32 v[12:13], v[208:209], v[4:5]
	v_pk_mul_f32 v[14:15], v[210:211], v[6:7]
	v_lshlrev_b32_e32 v0, 16, v84
	v_and_b32_e32 v1, s10, v84
	v_lshlrev_b32_e32 v2, 16, v85
	v_and_b32_e32 v3, s10, v85
	v_lshlrev_b32_e32 v4, 16, v86
	v_and_b32_e32 v5, s10, v86
	v_lshlrev_b32_e32 v6, 16, v87
	v_and_b32_e32 v7, s10, v87
	v_pk_fma_f32 v[8:9], v[212:213], v[0:1], v[8:9]
	v_pk_fma_f32 v[10:11], v[214:215], v[2:3], v[10:11]
	v_pk_fma_f32 v[12:13], v[216:217], v[4:5], v[12:13]
	v_pk_fma_f32 v[14:15], v[218:219], v[6:7], v[14:15]
	v_lshlrev_b32_e32 v0, 16, v88
	v_and_b32_e32 v1, s10, v88
	v_lshlrev_b32_e32 v2, 16, v89
	v_and_b32_e32 v3, s10, v89
	v_lshlrev_b32_e32 v4, 16, v90
	v_and_b32_e32 v5, s10, v90
	v_lshlrev_b32_e32 v6, 16, v91
	v_and_b32_e32 v7, s10, v91
	v_pk_fma_f32 v[8:9], v[220:221], v[0:1], v[8:9]
	v_pk_fma_f32 v[10:11], v[222:223], v[2:3], v[10:11]
	v_pk_fma_f32 v[12:13], v[224:225], v[4:5], v[12:13]
	v_pk_fma_f32 v[14:15], v[226:227], v[6:7], v[14:15]
	v_lshlrev_b32_e32 v0, 16, v92
	v_and_b32_e32 v1, s10, v92
	v_lshlrev_b32_e32 v2, 16, v93
	v_and_b32_e32 v3, s10, v93
	v_lshlrev_b32_e32 v4, 16, v94
	v_and_b32_e32 v5, s10, v94
	v_lshlrev_b32_e32 v6, 16, v95
	v_and_b32_e32 v7, s10, v95
	v_pk_fma_f32 v[8:9], v[228:229], v[0:1], v[8:9]
	v_pk_fma_f32 v[10:11], v[230:231], v[2:3], v[10:11]
	v_pk_fma_f32 v[12:13], v[232:233], v[4:5], v[12:13]
	v_pk_fma_f32 v[14:15], v[234:235], v[6:7], v[14:15]
	v_pk_mul_f32 v[16:17], v[8:9], v[252:253]
	v_pk_mul_f32 v[18:19], v[10:11], v[252:253]
	v_pk_mul_f32 v[20:21], v[12:13], v[252:253]
	v_pk_mul_f32 v[22:23], v[14:15], v[252:253]
	v_exp_f32_e32 v16, v16
	v_exp_f32_e32 v17, v17
	v_exp_f32_e32 v18, v18
	v_exp_f32_e32 v19, v19
	v_exp_f32_e32 v20, v20
	v_exp_f32_e32 v21, v21
	v_exp_f32_e32 v22, v22
	v_exp_f32_e32 v23, v23
	v_pk_add_f32 v[16:17], v[16:17], s[14:15]
	v_pk_add_f32 v[18:19], v[18:19], s[14:15]
	v_pk_add_f32 v[20:21], v[20:21], s[14:15]
	v_pk_add_f32 v[22:23], v[22:23], s[14:15]
	v_rcp_f32_e32 v16, v16
	v_rcp_f32_e32 v17, v17
	v_rcp_f32_e32 v18, v18
	v_rcp_f32_e32 v19, v19
	v_rcp_f32_e32 v20, v20
	v_rcp_f32_e32 v21, v21
	v_rcp_f32_e32 v22, v22
	v_rcp_f32_e32 v23, v23
	s_nop 0
	v_pk_mul_f32 v[244:245], v[8:9], v[16:17]
	v_pk_mul_f32 v[246:247], v[10:11], v[18:19]
	v_pk_mul_f32 v[248:249], v[12:13], v[20:21]
	v_pk_mul_f32 v[250:251], v[14:15], v[22:23]
	v_pk_mul_f32 v[16:17], v[236:237], v[236:237]
	v_pk_fma_f32 v[16:17], v[238:239], v[238:239], v[16:17]
	v_pk_fma_f32 v[16:17], v[240:241], v[240:241], v[16:17]
	v_pk_fma_f32 v[16:17], v[242:243], v[242:243], v[16:17]
	v_pk_fma_f32 v[16:17], v[244:245], v[244:245], v[16:17]
	v_pk_fma_f32 v[16:17], v[246:247], v[246:247], v[16:17]
	v_pk_fma_f32 v[16:17], v[248:249], v[248:249], v[16:17]
	v_pk_fma_f32 v[16:17], v[250:251], v[250:251], v[16:17]
	v_add_f32_e32 v25, v16, v17
	s_nop 1
	v_add_f32_dpp v25, v25, v25 quad_perm:[1,0,3,2] row_mask:0xf bank_mask:0xf bound_ctrl:1
	s_nop 1
	v_add_f32_dpp v25, v25, v25 quad_perm:[2,3,0,1] row_mask:0xf bank_mask:0xf bound_ctrl:1
	s_nop 1
	v_add_f32_dpp v25, v25, v25 row_half_mirror row_mask:0xf bank_mask:0xf bound_ctrl:1
	v_add_f32_e32 v25, 0x358637bd, v25
	v_rsq_f32_e32 v60, v25
	s_nop 0
	v_mul_f32_e32 v60, 0x3db504f3, v60
	v_pk_mul_f32 v[236:237], v[236:237], v[60:61] op_sel_hi:[1,0]
	v_pk_mul_f32 v[238:239], v[238:239], v[60:61] op_sel_hi:[1,0]
	v_pk_mul_f32 v[240:241], v[240:241], v[60:61] op_sel_hi:[1,0]
	v_pk_mul_f32 v[242:243], v[242:243], v[60:61] op_sel_hi:[1,0]
	v_pk_mul_f32 v[244:245], v[244:245], v[60:61] op_sel_hi:[1,0]
	v_pk_mul_f32 v[246:247], v[246:247], v[60:61] op_sel_hi:[1,0]
	v_pk_mul_f32 v[248:249], v[248:249], v[60:61] op_sel_hi:[1,0]
	v_pk_mul_f32 v[250:251], v[250:251], v[60:61] op_sel_hi:[1,0]
	v_cvt_pk_bf16_f32 v28, v236, v237
	v_cvt_pk_bf16_f32 v29, v238, v239
	v_cvt_pk_bf16_f32 v30, v240, v241
	v_cvt_pk_bf16_f32 v31, v242, v243
	ds_write_b128 v37, v[28:31] offset:17408
	v_cvt_pk_bf16_f32 v28, v244, v245
	v_cvt_pk_bf16_f32 v29, v246, v247
	v_cvt_pk_bf16_f32 v30, v248, v249
	v_cvt_pk_bf16_f32 v31, v250, v251
	ds_write_b128 v37, v[28:31] offset:17424
	v_pk_mul_f32 v[8:9], v[236:237], v[52:53] op_sel_hi:[1,0]
	v_pk_mul_f32 v[10:11], v[238:239], v[52:53] op_sel_hi:[1,0]
	v_pk_mul_f32 v[12:13], v[240:241], v[52:53] op_sel_hi:[1,0]
	v_pk_mul_f32 v[14:15], v[242:243], v[52:53] op_sel_hi:[1,0]
	v_cvt_pk_bf16_f32 v28, v8, v9
	v_cvt_pk_bf16_f32 v29, v10, v11
	v_cvt_pk_bf16_f32 v30, v12, v13
	v_cvt_pk_bf16_f32 v31, v14, v15
	v_pk_mul_f32 v[8:9], v[244:245], v[52:53] op_sel_hi:[1,0]
	v_pk_mul_f32 v[10:11], v[246:247], v[52:53] op_sel_hi:[1,0]
	v_pk_mul_f32 v[12:13], v[248:249], v[52:53] op_sel_hi:[1,0]
	v_pk_mul_f32 v[14:15], v[250:251], v[52:53] op_sel_hi:[1,0]
	v_cvt_pk_bf16_f32 v32, v8, v9
	v_cvt_pk_bf16_f32 v33, v10, v11
	v_cvt_pk_bf16_f32 v34, v12, v13
	v_cvt_pk_bf16_f32 v35, v14, v15
	global_store_dwordx4 v39, v[28:31], s[8:9]
	global_store_dwordx4 v39, v[32:35], s[8:9] offset:16
	v_and_b32_e32 v59, 15, v55
	v_or_b32_e32 v65, s34, v59
	v_lshlrev_b32_e32 v32, 6, v65
	v_ashrrev_i32_e32 v33, 31, v32
	v_lshrrev_b32_e32 v62, 4, v56
	v_lshlrev_b64 v[32:33], 1, v[32:33]
	v_lshlrev_b32_e32 v75, 2, v62
	v_add_u32_e32 v64, 0x15400, v58
	v_lshl_add_u32 v66, v65, 2, v63
	v_and_b32_e32 v61, 48, v55
	v_lshrrev_b32_e32 v60, 1, v61
	v_add_u32_e32 v57, 0x11000, v58
	s_waitcnt lgkmcnt(0)
	s_barrier
	v_or_b32_e32 v32, v32, v60
	v_mul_lo_u32 v0, v65, s51
	v_and_b32_e32 v1, 48, v56
	v_add3_u32 v12, v58, v0, v1
	ds_read_b128 v[24:27], v12
	ds_read_b128 v[4:7], v12 offset:64
	ds_read_b128 v[28:31], v12 offset:17408
	ds_read_b128 v[16:19], v12 offset:17472
	ds_read_b128 v[8:11], v12 offset:128
	ds_read_b128 v[0:3], v12 offset:192
	ds_read_b128 v[20:23], v12 offset:17536
	ds_read_b128 v[12:15], v12 offset:17600
	v_or_b32_e32 v72, s34, v75
	v_lshl_add_u64 v[32:33], s[28:29], 0, v[32:33]
	v_lshl_add_u64 v[50:51], v[40:41], 0, v[32:33]
	s_mov_b64 s[6:7], 0x22408000
	v_or_b32_e32 v71, 1, v72
	v_or_b32_e32 v69, 2, v72
	v_or_b32_e32 v67, 3, v72
	v_add_u32_e32 v76, v58, v61
	v_lshl_add_u64 v[52:53], v[50:51], 0, s[6:7]
	s_mov_b64 s[6:7], -1
	s_andn2_b64 vcc, exec, s[18:19]
	v_lshl_add_u32 v74, v72, 2, v63
	v_lshl_add_u32 v73, v71, 2, v63
	v_lshl_add_u32 v70, v69, 2, v63
	v_lshl_add_u32 v68, v67, 2, v63
	s_cbranch_vccz .LBB0_427
	v_lshl_add_u32 v33, v59, 2, v64
	s_andn2_b64 vcc, exec, s[6:7]
	v_lshlrev_b32_e32 v32, 8, v72
	s_cbranch_vccz .LBB0_428
